# deferred weight items moved from the bandwidth-bound MIX2 phase into G1's slack workgroups; their cache-copy rounds moved to layer-1 G4/G5 idle workgroups
# speedup vs baseline: 1.0020x; 1.0020x over previous
.LBB0_1094:
	s_mov_b64 exec, -1
	v_readlane_b32 s44, v251, 4
	v_readlane_b32 s45, v254, 42
	v_lshrrev_b32_e32 v4, 6, v178
	s_lshr_b32 s45, s45, 3
	v_readfirstlane_b32 s46, v4
	s_cmp_ge_i32 s44, 11
	s_cselect_b32 s47, 1, 0
	s_mul_i32 s48, s47, 10
	s_sub_i32 s48, s44, s48
	s_lshl_b32 s49, s47, 12
	s_and_b32 s54, s45, 1
	s_cmp_eq_u32 s54, s47
	s_cselect_b32 s54, 1, 0
	s_mov_b32 s50, 1
	s_mov_b32 s52, 0
	s_movk_i32 s53, 0x1000
	s_mov_b32 s66, 0x4000
	s_mov_b32 s67, 255
	s_mov_b32 s68, 0
	v_readlane_b32 s55, v251, 8
	s_cmp_lg_u32 s55, 0
	s_cbranch_scc1 .Lsc_std
	s_cmp_lg_u32 s44, 20
	s_cbranch_scc1 .Lsc_done
	s_mov_b32 s49, 0
	s_lshl_b32 s51, s45, 3
	s_movk_i32 s50, 0x2000
	s_mov_b32 s52, s6
	s_movk_i32 s53, 0x2000
	s_branch .Lsc_go

.Lsc_g1:
	s_sub_i32 s55, s45, 223
	s_cmp_lt_i32 s55, 0
	s_cbranch_scc1 .Lsc_done
	s_lshl_b32 s55, s55, 3
	s_add_i32 s55, s55, s46
	s_movk_i32 s30, 264
	s_mul_i32 s69, s47, 0x1200
	s_add_i32 s64, s69, 0x7c0
	s_add_i32 s31, s69, 0xad8
	s_branch .Lsc_wt_go

.Lsc_par:
	s_cmp_lt_i32 s55, 0
	s_cbranch_scc1 .Lsc_done
	s_lshr_b32 s55, s55, 1
	s_lshl_b32 s55, s55, 3
	s_cmp_eq_u32 s54, 0
	s_cbranch_scc1 .Lsc_odd
	s_add_i32 s51, s51, s55
	s_branch .Lsc_go
.Lsc_odd:
	s_add_i32 s55, s55, s46
	s_movk_i32 s30, 0x4000
	s_mul_i32 s69, s47, 0x1200
	s_cmp_eq_u32 s48, 5
	s_cbranch_scc0 .Lsc_odd3
	s_add_i32 s64, s69, 0xc50
	s_add_i32 s31, s69, 0x1000
	s_branch .Lsc_wt_go

.Lsc_odd4:
	s_cmp_lg_u32 s47, 0
	s_cbranch_scc1 .Lsc_odd4b
	s_movk_i32 s64, 0x13c0
	s_movk_i32 s31, 0x16c0
	s_cmp_eq_u32 s48, 8
	s_cbranch_scc1 .Lsc_wt_go
	s_movk_i32 s64, 0x16c0
	s_movk_i32 s31, 0x19c0
	s_branch .Lsc_wt_go
.Lsc_odd4b:
	s_sub_i32 s51, s55, s46
	s_add_i32 s51, s51, 3440
	s_movk_i32 s49, 0
	s_cmp_eq_u32 s48, 8
	s_cbranch_scc1 .Lsc_go
	s_movk_i32 s49, 0x1000
	s_branch .Lsc_go
.Lsc_m2:
	s_sub_i32 s55, s45, 225
	s_cmp_lt_u32 s45, 225
	s_cbranch_scc1 .Lsc_done
	s_lshl_b32 s55, s55, 3
	s_add_i32 s55, s55, s46
	s_movk_i32 s30, 248
	s_mul_i32 s69, s47, 0x1200
	s_add_i32 s64, s69, 0xad8
	s_add_i32 s31, s69, 0xc50

.Lwt_ret:
	s_mov_b32 s32, 0
	s_cmp_eq_u32 s68, 0
	s_cbranch_scc1 .Lsc_done
.Lsc_go:
	s_cmp_eq_u32 s67, 0
	s_cbranch_scc1 .Lsc_go2
	s_add_i32 s51, s51, s46
.Lsc_go2:
	v_readlane_b32 s56, v252, 4
	v_readlane_b32 s57, v252, 5
	v_readlane_b32 s58, v253, 62
	v_readlane_b32 s59, v253, 63
	s_add_u32 s56, s56, s66
	s_addc_u32 s57, s57, 0
	s_add_u32 s58, s58, 0xac80000
	s_addc_u32 s59, s59, 0
	s_add_u32 s58, s58, s66
	s_addc_u32 s59, s59, 0
	v_mbcnt_lo_u32_b32 v4, -1, 0
	v_mbcnt_hi_u32_b32 v4, -1, v4
	v_lshlrev_b32_e32 v4, 4, v4
	v_add_u32_e32 v5, 0x1000, v4
	v_add_u32_e32 v6, 0x2000, v4
	v_add_u32_e32 v7, 0x3000, v4
.Lsc_loop:
	s_cmp_ge_u32 s51, s53
	s_cbranch_scc1 .Lsc_done
	s_add_i32 s60, s49, s51
	s_and_b32 s62, s60, 127
	s_cmp_eq_u32 s62, s67
	s_cbranch_scc1 .Lsc_next
	s_lshr_b32 s61, s60, 7
	s_lshl_b32 s61, s61, 22
	s_lshl_b32 s62, s62, 15
	s_add_u32 s61, s61, s62
	s_add_u32 s62, s56, s61
	s_addc_u32 s63, s57, 0
	s_add_u32 s64, s58, s61
	s_addc_u32 s65, s59, 0
	global_load_dwordx4 v[8:11], v4, s[62:63] nt
	global_load_dwordx4 v[12:15], v4, s[62:63] offset:1024 nt
	global_load_dwordx4 v[16:19], v4, s[62:63] offset:2048 nt
	global_load_dwordx4 v[20:23], v4, s[62:63] offset:3072 nt
	global_load_dwordx4 v[24:27], v5, s[62:63] nt
	global_load_dwordx4 v[28:31], v5, s[62:63] offset:1024 nt
	global_load_dwordx4 v[32:35], v5, s[62:63] offset:2048 nt
	global_load_dwordx4 v[36:39], v5, s[62:63] offset:3072 nt
	global_load_dwordx4 v[40:43], v6, s[62:63] nt
	global_load_dwordx4 v[44:47], v6, s[62:63] offset:1024 nt
	global_load_dwordx4 v[48:51], v6, s[62:63] offset:2048 nt
	global_load_dwordx4 v[52:55], v6, s[62:63] offset:3072 nt
	global_load_dwordx4 v[56:59], v7, s[62:63] nt
	global_load_dwordx4 v[60:63], v7, s[62:63] offset:1024 nt
	global_load_dwordx4 v[64:67], v7, s[62:63] offset:2048 nt
	global_load_dwordx4 v[68:71], v7, s[62:63] offset:3072 nt
	s_waitcnt vmcnt(15)
	global_store_dwordx4 v4, v[8:11], s[64:65] nt
	s_waitcnt vmcnt(15)
	global_store_dwordx4 v4, v[12:15], s[64:65] offset:1024 nt
	s_waitcnt vmcnt(15)
	global_store_dwordx4 v4, v[16:19], s[64:65] offset:2048 nt
	s_waitcnt vmcnt(15)
	global_store_dwordx4 v4, v[20:23], s[64:65] offset:3072 nt
	s_waitcnt vmcnt(15)
	global_store_dwordx4 v5, v[24:27], s[64:65] nt
	s_waitcnt vmcnt(15)
	global_store_dwordx4 v5, v[28:31], s[64:65] offset:1024 nt
	s_waitcnt vmcnt(15)
	global_store_dwordx4 v5, v[32:35], s[64:65] offset:2048 nt
	s_waitcnt vmcnt(15)
	global_store_dwordx4 v5, v[36:39], s[64:65] offset:3072 nt
	s_waitcnt vmcnt(15)
	global_store_dwordx4 v6, v[40:43], s[64:65] nt
	s_waitcnt vmcnt(15)
	global_store_dwordx4 v6, v[44:47], s[64:65] offset:1024 nt
	s_waitcnt vmcnt(15)
	global_store_dwordx4 v6, v[48:51], s[64:65] offset:2048 nt
	s_waitcnt vmcnt(15)
	global_store_dwordx4 v6, v[52:55], s[64:65] offset:3072 nt
	s_waitcnt vmcnt(15)
	global_store_dwordx4 v7, v[56:59], s[64:65] nt
	s_waitcnt vmcnt(15)
	global_store_dwordx4 v7, v[60:63], s[64:65] offset:1024 nt
	s_waitcnt vmcnt(15)
	global_store_dwordx4 v7, v[64:67], s[64:65] offset:2048 nt
	s_waitcnt vmcnt(15)
	global_store_dwordx4 v7, v[68:71], s[64:65] offset:3072 nt
.Lsc_next:
	s_add_i32 s51, s51, s52
	s_add_i32 s50, s50, -1
	s_cmp_lg_u32 s50, 0
	s_cbranch_scc1 .Lsc_loop
